# KP table rewritten: coalesced loads + v_mfma_f32_16x16x4_f32 (exact f32) instead of 320 redundant loads per lane
# speedup vs baseline: 1.0462x; 1.0303x over previous
; __device__ __forceinline__ unsigned pk2(float lo, float hi) { f32x2_t v = {lo, hi}; bf16x2_t b = __builtin_convertvector(v, bf16x2_t); return __builtin_bit_cast(unsigned, b); }
; __device__ __forceinline__ void p1_tables(ArgsRef A, int tid, int first_block) {
;     ...
;       for (int i = gt; i < 32 * 64 * 64; i += NGT) { const int ln = i & 63, j = (i >> 6) & 63, g = i >> 12; const int c = ln & 15, kq = ln >> 4, jj = j - (kq >> 1), c0 = 8 * (kq & 1);
;         float acc[8];
; #pragma unroll
;         for (int k = 0; k < 8; ++k) acc[k] = 0.f;
;         if (jj >= 0) { const float* pw = PW + (size_t)((g * 65 + jj) * 64) * 2; const float* cr = Cre + (g * 16 + c) * 64; const float* ci = Cim + (g * 16 + c) * 64; const float* bb = BB + (size_t)(g * 64) * 32 + c0 * 2;
; #pragma unroll 4
;             for (int p = 0; p < 64; ++p) { const float xr = cr[p] * pw[2 * p] - ci[p] * pw[2 * p + 1], xi = cr[p] * pw[2 * p + 1] + ci[p] * pw[2 * p]; const f32x4* b4 = (const f32x4*)(bb + p * 32);
; #pragma unroll
;                 for (int k = 0; k < 4; ++k) { const f32x4 q = b4[k]; acc[2 * k] += xr * q.x - xi * q.y; acc[2 * k + 1] += xr * q.z - xi * q.w; } } }
;         u32x4 o; o.x = pk2(acc[0], acc[1]); o.y = pk2(acc[2], acc[3]); o.z = pk2(acc[4], acc[5]); o.w = pk2(acc[6], acc[7]);
;         *(u32x4*)(KP + (size_t)i * 8) = o; } }
.LBB0_164:
	s_mov_b64 s[36:37], exec
	v_readfirstlane_b32 s4, v0
	v_and_b32_e32 v1, 15, v0
	v_bfe_u32 v2, v0, 4, 2
	s_lshr_b32 s5, s4, 6
	s_and_b32 s23, s5, 63
	s_lshr_b32 s24, s5, 6
	v_lshlrev_b32_e32 v3, 8, v1
	v_lshl_add_u32 v3, v2, 6, v3
	s_lshl_b32 s25, s24, 12
	v_add_u32_e32 v3, s25, v3
	global_load_dwordx4 v[110:113], v3, s[44:45]
	global_load_dwordx4 v[114:117], v3, s[44:45] offset:16
	global_load_dwordx4 v[118:121], v3, s[44:45] offset:32
	global_load_dwordx4 v[122:125], v3, s[44:45] offset:48
	global_load_dwordx4 v[126:129], v3, s[46:47]
	global_load_dwordx4 v[130:133], v3, s[46:47] offset:16
	global_load_dwordx4 v[134:137], v3, s[46:47] offset:32
	global_load_dwordx4 v[138:141], v3, s[46:47] offset:48
	s_mul_i32 s25, s24, 0x41
	s_add_i32 s25, s25, s23
	s_lshl_b32 s25, s25, 9
	s_add_u32 s48, s26, 0x1880000
	s_addc_u32 s49, s27, 0
	v_lshlrev_b32_e32 v4, 7, v2
	v_add_u32_e32 v4, s25, v4
	global_load_dwordx4 v[146:149], v4, s[48:49]
	global_load_dwordx4 v[150:153], v4, s[48:49] offset:16
	global_load_dwordx4 v[154:157], v4, s[48:49] offset:32
	global_load_dwordx4 v[158:161], v4, s[48:49] offset:48
	global_load_dwordx4 v[162:165], v4, s[48:49] offset:64
	global_load_dwordx4 v[166:169], v4, s[48:49] offset:80
	global_load_dwordx4 v[170:173], v4, s[48:49] offset:96
	global_load_dwordx4 v[174:177], v4, s[48:49] offset:112
	global_load_dwordx4 v[178:181], v4, s[48:49] offset:-512
	global_load_dwordx4 v[182:185], v4, s[48:49] offset:-496
	global_load_dwordx4 v[186:189], v4, s[48:49] offset:-480
	global_load_dwordx4 v[190:193], v4, s[48:49] offset:-464
	global_load_dwordx4 v[194:197], v4, s[48:49] offset:-448
	global_load_dwordx4 v[198:201], v4, s[48:49] offset:-432
	global_load_dwordx4 v[202:205], v4, s[48:49] offset:-416
	global_load_dwordx4 v[206:209], v4, s[48:49] offset:-400
	s_add_u32 s52, s26, 0x2c00000
	s_addc_u32 s53, s27, 0
	v_lshlrev_b32_e32 v5, 3, v1
	v_lshl_add_u32 v5, v2, 11, v5
	s_lshl_b32 s25, s24, 13
	v_add_u32_e32 v5, s25, v5
	global_load_dwordx2 v[214:215], v5, s[52:53]
	global_load_dwordx2 v[216:217], v5, s[52:53] offset:128
	global_load_dwordx2 v[218:219], v5, s[52:53] offset:256
	global_load_dwordx2 v[220:221], v5, s[52:53] offset:384
	global_load_dwordx2 v[222:223], v5, s[52:53] offset:512
	global_load_dwordx2 v[224:225], v5, s[52:53] offset:640
	global_load_dwordx2 v[226:227], v5, s[52:53] offset:768
	global_load_dwordx2 v[228:229], v5, s[52:53] offset:896
	global_load_dwordx2 v[230:231], v5, s[52:53] offset:1024
	global_load_dwordx2 v[232:233], v5, s[52:53] offset:1152
	global_load_dwordx2 v[234:235], v5, s[52:53] offset:1280
	global_load_dwordx2 v[236:237], v5, s[52:53] offset:1408
	global_load_dwordx2 v[238:239], v5, s[52:53] offset:1536
	global_load_dwordx2 v[240:241], v5, s[52:53] offset:1664
	global_load_dwordx2 v[242:243], v5, s[52:53] offset:1792
	global_load_dwordx2 v[244:245], v5, s[52:53] offset:1920
	v_lshlrev_b32_e32 v6, 2, v1
	v_lshl_add_u32 v6, v2, 8, v6
	v_add_u32_e32 v6, s51, v6
	v_lshrrev_b32_e32 v7, 1, v2
	v_and_b32_e32 v8, 1, v2
	v_lshlrev_b32_e32 v9, 6, v1
	v_lshl_add_u32 v9, v7, 10, v9
	v_lshl_add_u32 v9, v8, 5, v9
	v_add_u32_e32 v9, s51, v9
	s_waitcnt vmcnt(16)
	v_mul_f32_e32 v246, v110, v146
	v_mul_f32_e32 v247, v110, v147
	v_fma_f32 v246, -v126, v147, v246
	v_fma_f32 v147, -v126, v146, -v247
	v_mov_b32_e32 v146, v246
	v_mul_f32_e32 v246, v111, v148
	v_mul_f32_e32 v247, v111, v149
	v_fma_f32 v246, -v127, v149, v246
	v_fma_f32 v149, -v127, v148, -v247
	v_mov_b32_e32 v148, v246
	v_mul_f32_e32 v246, v112, v150
	v_mul_f32_e32 v247, v112, v151
	v_fma_f32 v246, -v128, v151, v246
	v_fma_f32 v151, -v128, v150, -v247
	v_mov_b32_e32 v150, v246
	v_mul_f32_e32 v246, v113, v152
	v_mul_f32_e32 v247, v113, v153
	v_fma_f32 v246, -v129, v153, v246
	v_fma_f32 v153, -v129, v152, -v247
	v_mov_b32_e32 v152, v246
	v_mul_f32_e32 v246, v114, v154
	v_mul_f32_e32 v247, v114, v155
	v_fma_f32 v246, -v130, v155, v246
	v_fma_f32 v155, -v130, v154, -v247
	v_mov_b32_e32 v154, v246
	v_mul_f32_e32 v246, v115, v156
	v_mul_f32_e32 v247, v115, v157
	v_fma_f32 v246, -v131, v157, v246
	v_fma_f32 v157, -v131, v156, -v247
	v_mov_b32_e32 v156, v246
	v_mul_f32_e32 v246, v116, v158
	v_mul_f32_e32 v247, v116, v159
	v_fma_f32 v246, -v132, v159, v246
	v_fma_f32 v159, -v132, v158, -v247
	v_mov_b32_e32 v158, v246
	v_mul_f32_e32 v246, v117, v160
	v_mul_f32_e32 v247, v117, v161
	v_fma_f32 v246, -v133, v161, v246
	v_fma_f32 v161, -v133, v160, -v247
	v_mov_b32_e32 v160, v246
	v_mul_f32_e32 v246, v118, v162
	v_mul_f32_e32 v247, v118, v163
	v_fma_f32 v246, -v134, v163, v246
	v_fma_f32 v163, -v134, v162, -v247
	v_mov_b32_e32 v162, v246
	v_mul_f32_e32 v246, v119, v164
	v_mul_f32_e32 v247, v119, v165
	v_fma_f32 v246, -v135, v165, v246
	v_fma_f32 v165, -v135, v164, -v247
	v_mov_b32_e32 v164, v246
	v_mul_f32_e32 v246, v120, v166
	v_mul_f32_e32 v247, v120, v167
	v_fma_f32 v246, -v136, v167, v246
	v_fma_f32 v167, -v136, v166, -v247
	v_mov_b32_e32 v166, v246
	v_mul_f32_e32 v246, v121, v168
	v_mul_f32_e32 v247, v121, v169
	v_fma_f32 v246, -v137, v169, v246
	v_fma_f32 v169, -v137, v168, -v247
	v_mov_b32_e32 v168, v246
	v_mul_f32_e32 v246, v122, v170
	v_mul_f32_e32 v247, v122, v171
	v_fma_f32 v246, -v138, v171, v246
	v_fma_f32 v171, -v138, v170, -v247
	v_mov_b32_e32 v170, v246
	v_mul_f32_e32 v246, v123, v172
	v_mul_f32_e32 v247, v123, v173
	v_fma_f32 v246, -v139, v173, v246
	v_fma_f32 v173, -v139, v172, -v247
	v_mov_b32_e32 v172, v246
	v_mul_f32_e32 v246, v124, v174
	v_mul_f32_e32 v247, v124, v175
	v_fma_f32 v246, -v140, v175, v246
	v_fma_f32 v175, -v140, v174, -v247
	v_mov_b32_e32 v174, v246
	v_mul_f32_e32 v246, v125, v176
	v_mul_f32_e32 v247, v125, v177
; __device__ __forceinline__ unsigned pk2(float lo, float hi) { f32x2_t v = {lo, hi}; bf16x2_t b = __builtin_convertvector(v, bf16x2_t); return __builtin_bit_cast(unsigned, b); }
; __device__ __forceinline__ void p1_tables(ArgsRef A, int tid, int first_block) {
;     ...
;       for (int i = gt; i < 32 * 64 * 64; i += NGT) { const int ln = i & 63, j = (i >> 6) & 63, g = i >> 12; const int c = ln & 15, kq = ln >> 4, jj = j - (kq >> 1), c0 = 8 * (kq & 1);
;         float acc[8];
; #pragma unroll
;         for (int k = 0; k < 8; ++k) acc[k] = 0.f;
;         if (jj >= 0) { const float* pw = PW + (size_t)((g * 65 + jj) * 64) * 2; const float* cr = Cre + (g * 16 + c) * 64; const float* ci = Cim + (g * 16 + c) * 64; const float* bb = BB + (size_t)(g * 64) * 32 + c0 * 2;
; #pragma unroll 4
;             for (int p = 0; p < 64; ++p) { const float xr = cr[p] * pw[2 * p] - ci[p] * pw[2 * p + 1], xi = cr[p] * pw[2 * p + 1] + ci[p] * pw[2 * p]; const f32x4* b4 = (const f32x4*)(bb + p * 32);
; #pragma unroll
;                 for (int k = 0; k < 4; ++k) { const f32x4 q = b4[k]; acc[2 * k] += xr * q.x - xi * q.y; acc[2 * k + 1] += xr * q.z - xi * q.w; } } }
;         u32x4 o; o.x = pk2(acc[0], acc[1]); o.y = pk2(acc[2], acc[3]); o.z = pk2(acc[4], acc[5]); o.w = pk2(acc[6], acc[7]);
;         *(u32x4*)(KP + (size_t)i * 8) = o; } }
	v_fma_f32 v246, -v141, v177, v246
	v_fma_f32 v177, -v141, v176, -v247
	v_mov_b32_e32 v176, v246
	v_mul_f32_e32 v246, v110, v178
	v_mul_f32_e32 v247, v110, v179
	v_fma_f32 v246, -v126, v179, v246
	v_fma_f32 v179, -v126, v178, -v247
	v_mov_b32_e32 v178, v246
	v_mul_f32_e32 v246, v111, v180
	v_mul_f32_e32 v247, v111, v181
	v_fma_f32 v246, -v127, v181, v246
	v_fma_f32 v181, -v127, v180, -v247
	v_mov_b32_e32 v180, v246
	v_mul_f32_e32 v246, v112, v182
	v_mul_f32_e32 v247, v112, v183
	v_fma_f32 v246, -v128, v183, v246
	v_fma_f32 v183, -v128, v182, -v247
	v_mov_b32_e32 v182, v246
	v_mul_f32_e32 v246, v113, v184
	v_mul_f32_e32 v247, v113, v185
	v_fma_f32 v246, -v129, v185, v246
	v_fma_f32 v185, -v129, v184, -v247
	v_mov_b32_e32 v184, v246
	v_mul_f32_e32 v246, v114, v186
	v_mul_f32_e32 v247, v114, v187
	v_fma_f32 v246, -v130, v187, v246
	v_fma_f32 v187, -v130, v186, -v247
	v_mov_b32_e32 v186, v246
	v_mul_f32_e32 v246, v115, v188
	v_mul_f32_e32 v247, v115, v189
	v_fma_f32 v246, -v131, v189, v246
	v_fma_f32 v189, -v131, v188, -v247
	v_mov_b32_e32 v188, v246
	v_mul_f32_e32 v246, v116, v190
	v_mul_f32_e32 v247, v116, v191
	v_fma_f32 v246, -v132, v191, v246
	v_fma_f32 v191, -v132, v190, -v247
	v_mov_b32_e32 v190, v246
	v_mul_f32_e32 v246, v117, v192
	v_mul_f32_e32 v247, v117, v193
	v_fma_f32 v246, -v133, v193, v246
	v_fma_f32 v193, -v133, v192, -v247
	v_mov_b32_e32 v192, v246
	v_mul_f32_e32 v246, v118, v194
	v_mul_f32_e32 v247, v118, v195
	v_fma_f32 v246, -v134, v195, v246
	v_fma_f32 v195, -v134, v194, -v247
	v_mov_b32_e32 v194, v246
	v_mul_f32_e32 v246, v119, v196
	v_mul_f32_e32 v247, v119, v197
	v_fma_f32 v246, -v135, v197, v246
	v_fma_f32 v197, -v135, v196, -v247
	v_mov_b32_e32 v196, v246
	v_mul_f32_e32 v246, v120, v198
	v_mul_f32_e32 v247, v120, v199
	v_fma_f32 v246, -v136, v199, v246
	v_fma_f32 v199, -v136, v198, -v247
	v_mov_b32_e32 v198, v246
	v_mul_f32_e32 v246, v121, v200
	v_mul_f32_e32 v247, v121, v201
	v_fma_f32 v246, -v137, v201, v246
	v_fma_f32 v201, -v137, v200, -v247
	v_mov_b32_e32 v200, v246
	v_mul_f32_e32 v246, v122, v202
	v_mul_f32_e32 v247, v122, v203
	v_fma_f32 v246, -v138, v203, v246
	v_fma_f32 v203, -v138, v202, -v247
	v_mov_b32_e32 v202, v246
	v_mul_f32_e32 v246, v123, v204
	v_mul_f32_e32 v247, v123, v205
	v_fma_f32 v246, -v139, v205, v246
	v_fma_f32 v205, -v139, v204, -v247
	v_mov_b32_e32 v204, v246
	v_mul_f32_e32 v246, v124, v206
	v_mul_f32_e32 v247, v124, v207
	v_fma_f32 v246, -v140, v207, v246
	v_fma_f32 v207, -v140, v206, -v247
	v_mov_b32_e32 v206, v246
	v_mul_f32_e32 v246, v125, v208
	v_mul_f32_e32 v247, v125, v209
	v_fma_f32 v246, -v141, v209, v246
	v_fma_f32 v209, -v141, v208, -v247
	v_mov_b32_e32 v208, v246
	s_waitcnt vmcnt(0)
	s_nop 1
	v_mfma_f32_16x16x4_f32 v[248:251], v146, v214, 0
	v_mfma_f32_16x16x4_f32 v[18:21], v178, v214, 0
	v_mfma_f32_16x16x4_f32 v[248:251], v147, v215, v[248:251]
	v_mfma_f32_16x16x4_f32 v[18:21], v179, v215, v[18:21]
	v_mfma_f32_16x16x4_f32 v[248:251], v148, v216, v[248:251]
	v_mfma_f32_16x16x4_f32 v[18:21], v180, v216, v[18:21]
	v_mfma_f32_16x16x4_f32 v[248:251], v149, v217, v[248:251]
	v_mfma_f32_16x16x4_f32 v[18:21], v181, v217, v[18:21]
	v_mfma_f32_16x16x4_f32 v[248:251], v150, v218, v[248:251]
	v_mfma_f32_16x16x4_f32 v[18:21], v182, v218, v[18:21]
	v_mfma_f32_16x16x4_f32 v[248:251], v151, v219, v[248:251]
	v_mfma_f32_16x16x4_f32 v[18:21], v183, v219, v[18:21]
	v_mfma_f32_16x16x4_f32 v[248:251], v152, v220, v[248:251]
	v_mfma_f32_16x16x4_f32 v[18:21], v184, v220, v[18:21]
	v_mfma_f32_16x16x4_f32 v[248:251], v153, v221, v[248:251]
	v_mfma_f32_16x16x4_f32 v[18:21], v185, v221, v[18:21]
	v_mfma_f32_16x16x4_f32 v[248:251], v154, v222, v[248:251]
	v_mfma_f32_16x16x4_f32 v[18:21], v186, v222, v[18:21]
	v_mfma_f32_16x16x4_f32 v[248:251], v155, v223, v[248:251]
	v_mfma_f32_16x16x4_f32 v[18:21], v187, v223, v[18:21]
	v_mfma_f32_16x16x4_f32 v[248:251], v156, v224, v[248:251]
	v_mfma_f32_16x16x4_f32 v[18:21], v188, v224, v[18:21]
	v_mfma_f32_16x16x4_f32 v[248:251], v157, v225, v[248:251]
	v_mfma_f32_16x16x4_f32 v[18:21], v189, v225, v[18:21]
	v_mfma_f32_16x16x4_f32 v[248:251], v158, v226, v[248:251]
	v_mfma_f32_16x16x4_f32 v[18:21], v190, v226, v[18:21]
	v_mfma_f32_16x16x4_f32 v[248:251], v159, v227, v[248:251]
	v_mfma_f32_16x16x4_f32 v[18:21], v191, v227, v[18:21]
	v_mfma_f32_16x16x4_f32 v[248:251], v160, v228, v[248:251]
	v_mfma_f32_16x16x4_f32 v[18:21], v192, v228, v[18:21]
	v_mfma_f32_16x16x4_f32 v[248:251], v161, v229, v[248:251]
	v_mfma_f32_16x16x4_f32 v[18:21], v193, v229, v[18:21]
	v_mfma_f32_16x16x4_f32 v[248:251], v162, v230, v[248:251]
	v_mfma_f32_16x16x4_f32 v[18:21], v194, v230, v[18:21]
	v_mfma_f32_16x16x4_f32 v[248:251], v163, v231, v[248:251]
	v_mfma_f32_16x16x4_f32 v[18:21], v195, v231, v[18:21]
	v_mfma_f32_16x16x4_f32 v[248:251], v164, v232, v[248:251]
	v_mfma_f32_16x16x4_f32 v[18:21], v196, v232, v[18:21]
	v_mfma_f32_16x16x4_f32 v[248:251], v165, v233, v[248:251]
	v_mfma_f32_16x16x4_f32 v[18:21], v197, v233, v[18:21]
	v_mfma_f32_16x16x4_f32 v[248:251], v166, v234, v[248:251]
	v_mfma_f32_16x16x4_f32 v[18:21], v198, v234, v[18:21]
	v_mfma_f32_16x16x4_f32 v[248:251], v167, v235, v[248:251]
	v_mfma_f32_16x16x4_f32 v[18:21], v199, v235, v[18:21]
	v_mfma_f32_16x16x4_f32 v[248:251], v168, v236, v[248:251]
	v_mfma_f32_16x16x4_f32 v[18:21], v200, v236, v[18:21]
	v_mfma_f32_16x16x4_f32 v[248:251], v169, v237, v[248:251]
	v_mfma_f32_16x16x4_f32 v[18:21], v201, v237, v[18:21]
	v_mfma_f32_16x16x4_f32 v[248:251], v170, v238, v[248:251]
	v_mfma_f32_16x16x4_f32 v[18:21], v202, v238, v[18:21]
	v_mfma_f32_16x16x4_f32 v[248:251], v171, v239, v[248:251]
	v_mfma_f32_16x16x4_f32 v[18:21], v203, v239, v[18:21]
	v_mfma_f32_16x16x4_f32 v[248:251], v172, v240, v[248:251]
	v_mfma_f32_16x16x4_f32 v[18:21], v204, v240, v[18:21]
	v_mfma_f32_16x16x4_f32 v[248:251], v173, v241, v[248:251]
	v_mfma_f32_16x16x4_f32 v[18:21], v205, v241, v[18:21]
	v_mfma_f32_16x16x4_f32 v[248:251], v174, v242, v[248:251]
	v_mfma_f32_16x16x4_f32 v[18:21], v206, v242, v[18:21]
	v_mfma_f32_16x16x4_f32 v[248:251], v175, v243, v[248:251]
	v_mfma_f32_16x16x4_f32 v[18:21], v207, v243, v[18:21]
	v_mfma_f32_16x16x4_f32 v[248:251], v176, v244, v[248:251]
	v_mfma_f32_16x16x4_f32 v[18:21], v208, v244, v[18:21]
	v_mfma_f32_16x16x4_f32 v[248:251], v177, v245, v[248:251]
	v_mfma_f32_16x16x4_f32 v[18:21], v209, v245, v[18:21]
	s_nop 7
	s_nop 7
	s_cmp_lg_u32 s23, 0
	s_cbranch_scc1 .Lkp2_nz
	v_mov_b32_e32 v18, 0
	v_mov_b32_e32 v19, 0
	v_mov_b32_e32 v20, 0
	v_mov_b32_e32 v21, 0
.Lkp2_nz:
	ds_write_b32 v6, v248
	ds_write_b32 v6, v249 offset:64
	ds_write_b32 v6, v250 offset:128
	ds_write_b32 v6, v251 offset:192
	ds_write_b32 v6, v18 offset:1024
	ds_write_b32 v6, v19 offset:1088
	ds_write_b32 v6, v20 offset:1152
	ds_write_b32 v6, v21 offset:1216
	s_waitcnt lgkmcnt(0)
	ds_read_b128 v[10:13], v9
	ds_read_b128 v[14:17], v9 offset:16
	s_waitcnt lgkmcnt(0)
	v_mov_b32_e32 v8, v14
	v_mov_b32_e32 v9, v15
	v_mov_b32_e32 v2, v16
	v_mov_b32_e32 v3, v17
	s_branch .LBB0_163
